# v28 + NSA selected loop: selection mask folded into the reference (m' = mask ? 1e30 : m), bias loaded straight into the MFMA C registers, one v_sub per element instead of v_sub + v_cndmask
# baseline (speedup 1.0000x reference)
; #define LAS __attribute__((address_space(3)))
;     ...
;         } else { LAS const float* ab = aux + (t - kb + 1);
; #pragma unroll
;             for (int r = 0; r < 16; ++r) { X0[r] = ab[63 - ((r & 3) + 8 * (r >> 2))] - m; X1[r] = ab[31 - ((r & 3) + 8 * (r >> 2))] - m; }
;             if (MODE == 1 && !sel) {
; #pragma unroll
;                 for (int r = 0; r < 16; ++r) { X0[r] = NEG; X1[r] = NEG; } }
.LBB0_983:
	s_andn2_b64 vcc, exec, s[8:9]
	s_cbranch_vccnz .LBB0_985
	v_lshl_or_b32 v2, s97, 6, v179
	v_sub_u32_e32 v2, v178, v2
	v_mov_b32_e32 v225, 0x7149f2ca
	s_nop 7
	v_lshl_add_u32 v224, v2, 2, s96
	v_cndmask_b32_e64 v225, v0, v225, s[4:5]
	ds_read2_b32 v[128:129], v224 offset0:64 offset1:63
	ds_read2_b32 v[130:131], v224 offset0:62 offset1:61
	ds_read2_b32 v[132:133], v224 offset0:56 offset1:55
	ds_read2_b32 v[134:135], v224 offset0:54 offset1:53
	ds_read2_b32 v[136:137], v224 offset0:48 offset1:47
	ds_read2_b32 v[138:139], v224 offset0:46 offset1:45
	ds_read2_b32 v[140:141], v224 offset0:40 offset1:39
	ds_read2_b32 v[142:143], v224 offset0:38 offset1:37
	ds_read2_b32 v[112:113], v224 offset0:32 offset1:31
	ds_read2_b32 v[114:115], v224 offset0:30 offset1:29
	ds_read2_b32 v[116:117], v224 offset0:24 offset1:23
	ds_read2_b32 v[118:119], v224 offset0:22 offset1:21
	ds_read2_b32 v[120:121], v224 offset0:16 offset1:15
	ds_read2_b32 v[122:123], v224 offset0:14 offset1:13
	ds_read2_b32 v[124:125], v224 offset0:8 offset1:7
	ds_read2_b32 v[126:127], v224 offset0:6 offset1:5
	s_add_i32 s8, s51, 0
	s_waitcnt lgkmcnt(12)
	v_sub_f32_e32 v128, v128, v225
	v_sub_f32_e32 v129, v129, v225
	v_sub_f32_e32 v130, v130, v225
	v_sub_f32_e32 v131, v131, v225
	v_sub_f32_e32 v132, v132, v225
	v_sub_f32_e32 v133, v133, v225
	v_sub_f32_e32 v134, v134, v225
	v_sub_f32_e32 v135, v135, v225
	s_waitcnt lgkmcnt(8)
	v_sub_f32_e32 v136, v136, v225
	v_sub_f32_e32 v137, v137, v225
	v_sub_f32_e32 v138, v138, v225
	v_sub_f32_e32 v139, v139, v225
	v_sub_f32_e32 v140, v140, v225
	v_sub_f32_e32 v141, v141, v225
	v_sub_f32_e32 v142, v142, v225
	v_sub_f32_e32 v143, v143, v225
	v_add_u32_e32 v8, s8, v183
	ds_read_b128 v[2:5], v8
	ds_read_b128 v[6:9], v8 offset:4096
	v_add_u32_e32 v194, s8, v184
	v_add_u32_e32 v195, s8, v186
	v_add_u32_e32 v212, s8, v187
	ds_read_b128 v[196:199], v194
	ds_read_b128 v[200:203], v194 offset:4096
	ds_read_b128 v[204:207], v195
	ds_read_b128 v[208:211], v195 offset:4096
	ds_read_b128 v[216:219], v212
	ds_read_b128 v[220:223], v212 offset:4096
	s_waitcnt lgkmcnt(12)
	v_sub_f32_e32 v112, v112, v225
	v_sub_f32_e32 v113, v113, v225
	v_sub_f32_e32 v114, v114, v225
	v_sub_f32_e32 v115, v115, v225
	v_sub_f32_e32 v116, v116, v225
	v_sub_f32_e32 v117, v117, v225
	v_sub_f32_e32 v118, v118, v225
	v_sub_f32_e32 v119, v119, v225
	s_waitcnt lgkmcnt(8)
	v_sub_f32_e32 v120, v120, v225
	v_sub_f32_e32 v121, v121, v225
	v_sub_f32_e32 v122, v122, v225
	v_sub_f32_e32 v123, v123, v225
	v_sub_f32_e32 v124, v124, v225
	v_sub_f32_e32 v125, v125, v225
	v_sub_f32_e32 v126, v126, v225
	v_sub_f32_e32 v127, v127, v225
	s_waitcnt lgkmcnt(6)
	v_mfma_f32_32x32x16_bf16 v[128:143], v[2:5], v[144:147], v[128:143]
	v_mfma_f32_32x32x16_bf16 v[112:127], v[6:9], v[144:147], v[112:127]
	s_waitcnt lgkmcnt(4)
	v_mfma_f32_32x32x16_bf16 v[128:143], v[196:199], v[148:151], v[128:143]
	v_mfma_f32_32x32x16_bf16 v[112:127], v[200:203], v[148:151], v[112:127]
	s_waitcnt lgkmcnt(2)
	v_mfma_f32_32x32x16_bf16 v[128:143], v[204:207], v[152:155], v[128:143]
	v_mfma_f32_32x32x16_bf16 v[112:127], v[208:211], v[152:155], v[112:127]
	s_waitcnt lgkmcnt(0)
	v_mfma_f32_32x32x16_bf16 v[128:143], v[216:219], v[156:159], v[128:143]
	v_mfma_f32_32x32x16_bf16 v[112:127], v[220:223], v[156:159], v[112:127]
